# k64 + the eight GEMM K-loop heads aligned to 64 bytes (code placement)
# speedup vs baseline: 1.0104x; 1.0059x over previous
.LBB0_199:
	s_ashr_i32 s17, s16, 31
	s_lshl_b64 s[18:19], s[16:17], 21
	s_add_u32 s18, s37, s18
	s_addc_u32 s19, s38, s19
	s_and_b64 s[20:21], s[4:5], exec
	s_cselect_b32 s17, s19, s7
	s_cselect_b32 s23, s18, s6
	s_ashr_i32 s15, s14, 31
	s_lshl_b64 s[20:21], s[14:15], 21
	s_add_u32 s20, s39, s20
	s_addc_u32 s21, s40, s21
	s_and_b64 s[28:29], s[4:5], exec
	s_cselect_b32 s15, s21, s27
	s_cselect_b32 s25, s20, s26
	s_add_u32 s6, s6, 0x100800
	s_addc_u32 s7, s7, 0
	s_add_u32 s30, s26, 0x1000
	v_mov_b32_e32 v0, 0
	s_addc_u32 s31, s27, 0
	s_mov_b32 s34, -2
	s_waitcnt lgkmcnt(0)
	v_mov_b32_e32 v1, v0
	v_mov_b32_e32 v2, v0
	v_mov_b32_e32 v3, v0
	v_mov_b32_e32 v4, v0
	v_mov_b32_e32 v5, v0
	v_mov_b32_e32 v6, v0
	v_mov_b32_e32 v7, v0
	v_mov_b32_e32 v8, v0
	v_mov_b32_e32 v9, v0
	v_mov_b32_e32 v10, v0
	v_mov_b32_e32 v11, v0
	v_mov_b32_e32 v12, v0
	v_mov_b32_e32 v13, v0
	v_mov_b32_e32 v14, v0
	v_mov_b32_e32 v15, v0
	v_mov_b32_e32 v16, v0
	v_mov_b32_e32 v17, v0
	v_mov_b32_e32 v18, v0
	v_mov_b32_e32 v19, v0
	v_mov_b32_e32 v20, v0
	v_mov_b32_e32 v21, v0
	v_mov_b32_e32 v22, v0
	v_mov_b32_e32 v23, v0
	v_mov_b32_e32 v24, v0
	v_mov_b32_e32 v25, v0
	v_mov_b32_e32 v26, v0
	v_mov_b32_e32 v27, v0
	v_mov_b32_e32 v28, v0
	v_mov_b32_e32 v29, v0
	v_mov_b32_e32 v30, v0
	v_mov_b32_e32 v31, v0
	v_mov_b32_e32 v64, v0
	v_mov_b32_e32 v65, v0
	v_mov_b32_e32 v66, v0
	v_mov_b32_e32 v67, v0
	v_mov_b32_e32 v68, v0
	v_mov_b32_e32 v69, v0
	v_mov_b32_e32 v70, v0
	v_mov_b32_e32 v71, v0
	v_mov_b32_e32 v72, v0
	v_mov_b32_e32 v73, v0
	v_mov_b32_e32 v74, v0
	v_mov_b32_e32 v75, v0
	v_mov_b32_e32 v76, v0
	v_mov_b32_e32 v77, v0
	v_mov_b32_e32 v78, v0
	v_mov_b32_e32 v79, v0
	v_mov_b32_e32 v80, v0
	v_mov_b32_e32 v81, v0
	v_mov_b32_e32 v82, v0
	v_mov_b32_e32 v83, v0
	v_mov_b32_e32 v84, v0
	v_mov_b32_e32 v85, v0
	v_mov_b32_e32 v86, v0
	v_mov_b32_e32 v87, v0
	v_mov_b32_e32 v88, v0
	v_mov_b32_e32 v89, v0
	v_mov_b32_e32 v90, v0
	v_mov_b32_e32 v91, v0
	v_mov_b32_e32 v92, v0
	v_mov_b32_e32 v93, v0
	v_mov_b32_e32 v94, v0
	v_mov_b32_e32 v95, v0
	v_mov_b32_e32 v32, v0
	v_mov_b32_e32 v33, v0
	v_mov_b32_e32 v34, v0
	v_mov_b32_e32 v35, v0
	v_mov_b32_e32 v36, v0
	v_mov_b32_e32 v37, v0
	v_mov_b32_e32 v38, v0
	v_mov_b32_e32 v39, v0
	v_mov_b32_e32 v40, v0
	v_mov_b32_e32 v41, v0
	v_mov_b32_e32 v42, v0
	v_mov_b32_e32 v43, v0
	v_mov_b32_e32 v44, v0
	v_mov_b32_e32 v45, v0
	v_mov_b32_e32 v46, v0
	v_mov_b32_e32 v47, v0
	v_mov_b32_e32 v48, v0
	v_mov_b32_e32 v49, v0
	v_mov_b32_e32 v50, v0
	v_mov_b32_e32 v51, v0
	v_mov_b32_e32 v52, v0
	v_mov_b32_e32 v53, v0
	v_mov_b32_e32 v54, v0
	v_mov_b32_e32 v55, v0
	v_mov_b32_e32 v56, v0
	v_mov_b32_e32 v57, v0
	v_mov_b32_e32 v58, v0
	v_mov_b32_e32 v59, v0
	v_mov_b32_e32 v60, v0
	v_mov_b32_e32 v61, v0
	v_mov_b32_e32 v62, v0
	v_mov_b32_e32 v63, v0
	v_mov_b32_e32 v96, v0
	v_mov_b32_e32 v97, v0
	v_mov_b32_e32 v98, v0
	v_mov_b32_e32 v99, v0
	v_mov_b32_e32 v100, v0
	v_mov_b32_e32 v101, v0
	v_mov_b32_e32 v102, v0
	v_mov_b32_e32 v103, v0
	v_mov_b32_e32 v104, v0
	v_mov_b32_e32 v105, v0
	v_mov_b32_e32 v106, v0
	v_mov_b32_e32 v107, v0
	v_mov_b32_e32 v108, v0
	v_mov_b32_e32 v109, v0
	v_mov_b32_e32 v110, v0
	v_mov_b32_e32 v111, v0
	v_mov_b32_e32 v112, v0
	v_mov_b32_e32 v113, v0
	v_mov_b32_e32 v114, v0
	v_mov_b32_e32 v115, v0
	v_mov_b32_e32 v116, v0
	v_mov_b32_e32 v117, v0
	v_mov_b32_e32 v118, v0
	v_mov_b32_e32 v119, v0
	v_mov_b32_e32 v120, v0
	v_mov_b32_e32 v121, v0
	v_mov_b32_e32 v122, v0
	v_mov_b32_e32 v123, v0
	v_mov_b32_e32 v124, v0
	v_mov_b32_e32 v125, v0
	v_mov_b32_e32 v126, v0
	v_mov_b32_e32 v127, v0
	.p2align 6

.LBB0_332:
	s_ashr_i32 s13, s12, 31
	s_lshl_b64 s[14:15], s[12:13], 21
	s_add_u32 s14, s37, s14
	s_addc_u32 s15, s38, s15
	s_and_b64 s[16:17], s[2:3], exec
	s_cselect_b32 s13, s15, s25
	s_cselect_b32 s52, s14, s24
	s_ashr_i32 s11, s10, 31
	s_lshl_b64 s[16:17], s[10:11], 21
	s_add_u32 s16, s39, s16
	s_addc_u32 s17, s40, s17
	s_and_b64 s[30:31], s[2:3], exec
	s_cselect_b32 s11, s17, s29
	s_cselect_b32 s53, s16, s28
	s_add_u32 s54, s28, 0x100
	v_mov_b32_e32 v0, 0
	s_addc_u32 s55, s29, 0
	s_mov_b32 s56, -2
	v_mov_b32_e32 v1, v0
	v_mov_b32_e32 v2, v0
	v_mov_b32_e32 v3, v0
	v_mov_b32_e32 v4, v0
	v_mov_b32_e32 v5, v0
	v_mov_b32_e32 v6, v0
	v_mov_b32_e32 v7, v0
	v_mov_b32_e32 v8, v0
	v_mov_b32_e32 v9, v0
	v_mov_b32_e32 v10, v0
	v_mov_b32_e32 v11, v0
	v_mov_b32_e32 v16, v0
	v_mov_b32_e32 v17, v0
	v_mov_b32_e32 v18, v0
	v_mov_b32_e32 v19, v0
	v_mov_b32_e32 v24, v0
	v_mov_b32_e32 v25, v0
	v_mov_b32_e32 v26, v0
	v_mov_b32_e32 v27, v0
	v_mov_b32_e32 v32, v0
	v_mov_b32_e32 v33, v0
	v_mov_b32_e32 v34, v0
	v_mov_b32_e32 v35, v0
	v_mov_b32_e32 v40, v0
	v_mov_b32_e32 v41, v0
	v_mov_b32_e32 v42, v0
	v_mov_b32_e32 v43, v0
	v_mov_b32_e32 v48, v0
	v_mov_b32_e32 v49, v0
	v_mov_b32_e32 v50, v0
	v_mov_b32_e32 v51, v0
	v_mov_b32_e32 v12, v0
	v_mov_b32_e32 v13, v0
	v_mov_b32_e32 v14, v0
	v_mov_b32_e32 v15, v0
	v_mov_b32_e32 v20, v0
	v_mov_b32_e32 v21, v0
	v_mov_b32_e32 v22, v0
	v_mov_b32_e32 v23, v0
	v_mov_b32_e32 v28, v0
	v_mov_b32_e32 v29, v0
	v_mov_b32_e32 v30, v0
	v_mov_b32_e32 v31, v0
	v_mov_b32_e32 v36, v0
	v_mov_b32_e32 v37, v0
	v_mov_b32_e32 v38, v0
	v_mov_b32_e32 v39, v0
	v_mov_b32_e32 v44, v0
	v_mov_b32_e32 v45, v0
	v_mov_b32_e32 v46, v0
	v_mov_b32_e32 v47, v0
	v_mov_b32_e32 v52, v0
	v_mov_b32_e32 v53, v0
	v_mov_b32_e32 v54, v0
	v_mov_b32_e32 v55, v0
	v_mov_b32_e32 v56, v0
	v_mov_b32_e32 v57, v0
	v_mov_b32_e32 v58, v0
	v_mov_b32_e32 v59, v0
	v_mov_b32_e32 v60, v0
	v_mov_b32_e32 v61, v0
	v_mov_b32_e32 v62, v0
	v_mov_b32_e32 v63, v0
	v_mov_b32_e32 v64, v0
	v_mov_b32_e32 v65, v0
	v_mov_b32_e32 v66, v0
	v_mov_b32_e32 v67, v0
	v_mov_b32_e32 v68, v0
	v_mov_b32_e32 v69, v0
	v_mov_b32_e32 v70, v0
	v_mov_b32_e32 v71, v0
	v_mov_b32_e32 v72, v0
	v_mov_b32_e32 v73, v0
	v_mov_b32_e32 v74, v0
	v_mov_b32_e32 v75, v0
	v_mov_b32_e32 v80, v0
	v_mov_b32_e32 v81, v0
	v_mov_b32_e32 v82, v0
	v_mov_b32_e32 v83, v0
	v_mov_b32_e32 v88, v0
	v_mov_b32_e32 v89, v0
	v_mov_b32_e32 v90, v0
	v_mov_b32_e32 v91, v0
	v_mov_b32_e32 v96, v0
	v_mov_b32_e32 v97, v0
	v_mov_b32_e32 v98, v0
	v_mov_b32_e32 v99, v0
	v_mov_b32_e32 v104, v0
	v_mov_b32_e32 v105, v0
	v_mov_b32_e32 v106, v0
	v_mov_b32_e32 v107, v0
	v_mov_b32_e32 v112, v0
	v_mov_b32_e32 v113, v0
	v_mov_b32_e32 v114, v0
	v_mov_b32_e32 v115, v0
	v_mov_b32_e32 v76, v0
	v_mov_b32_e32 v77, v0
	v_mov_b32_e32 v78, v0
	v_mov_b32_e32 v79, v0
	v_mov_b32_e32 v84, v0
	v_mov_b32_e32 v85, v0
	v_mov_b32_e32 v86, v0
	v_mov_b32_e32 v87, v0
	v_mov_b32_e32 v92, v0
	v_mov_b32_e32 v93, v0
	v_mov_b32_e32 v94, v0
	v_mov_b32_e32 v95, v0
	v_mov_b32_e32 v100, v0
	v_mov_b32_e32 v101, v0
	v_mov_b32_e32 v102, v0
	v_mov_b32_e32 v103, v0
	v_mov_b32_e32 v108, v0
	v_mov_b32_e32 v109, v0
	v_mov_b32_e32 v110, v0
	v_mov_b32_e32 v111, v0
	v_mov_b32_e32 v116, v0
	v_mov_b32_e32 v117, v0
	v_mov_b32_e32 v118, v0
	v_mov_b32_e32 v119, v0
	v_mov_b32_e32 v120, v0
	v_mov_b32_e32 v121, v0
	v_mov_b32_e32 v122, v0
	v_mov_b32_e32 v123, v0
	v_mov_b32_e32 v124, v0
	v_mov_b32_e32 v125, v0
	v_mov_b32_e32 v126, v0
	v_mov_b32_e32 v127, v0
	.p2align 6

.LBB0_1201:
	s_ashr_i32 s23, s22, 31
	s_lshl_b64 s[24:25], s[22:23], 21
	s_add_u32 s24, s55, s24
	s_addc_u32 s25, s56, s25
	s_and_b64 s[26:27], s[4:5], exec
	s_cselect_b32 s23, s25, s31
	s_cselect_b32 s36, s24, s30
	s_ashr_i32 s21, s20, 31
	s_lshl_b64 s[26:27], s[20:21], 21
	s_add_u32 s26, s57, s26
	s_addc_u32 s27, s58, s27
	s_and_b64 s[34:35], s[4:5], exec
	s_cselect_b32 s21, s27, s29
	s_cselect_b32 s37, s26, s28
	s_add_u32 s38, s28, 0x1000
	s_addc_u32 s39, s29, 0
	s_add_u32 s28, s30, 0x100080
	v_mov_b32_e32 v0, 0
	s_addc_u32 s29, s31, 0
	s_mov_b32 s40, -2
	s_waitcnt lgkmcnt(0)
	v_mov_b32_e32 v1, v0
	v_mov_b32_e32 v2, v0
	v_mov_b32_e32 v3, v0
	v_mov_b32_e32 v4, v0
	v_mov_b32_e32 v5, v0
	v_mov_b32_e32 v6, v0
	v_mov_b32_e32 v7, v0
	v_mov_b32_e32 v16, v0
	v_mov_b32_e32 v17, v0
	v_mov_b32_e32 v18, v0
	v_mov_b32_e32 v19, v0
	v_mov_b32_e32 v20, v0
	v_mov_b32_e32 v21, v0
	v_mov_b32_e32 v22, v0
	v_mov_b32_e32 v23, v0
	v_mov_b32_e32 v32, v0
	v_mov_b32_e32 v33, v0
	v_mov_b32_e32 v34, v0
	v_mov_b32_e32 v35, v0
	v_mov_b32_e32 v36, v0
	v_mov_b32_e32 v37, v0
	v_mov_b32_e32 v38, v0
	v_mov_b32_e32 v39, v0
	v_mov_b32_e32 v48, v0
	v_mov_b32_e32 v49, v0
	v_mov_b32_e32 v50, v0
	v_mov_b32_e32 v51, v0
	v_mov_b32_e32 v52, v0
	v_mov_b32_e32 v53, v0
	v_mov_b32_e32 v54, v0
	v_mov_b32_e32 v55, v0
	v_mov_b32_e32 v8, v0
	v_mov_b32_e32 v9, v0
	v_mov_b32_e32 v10, v0
	v_mov_b32_e32 v11, v0
	v_mov_b32_e32 v12, v0
	v_mov_b32_e32 v13, v0
	v_mov_b32_e32 v14, v0
	v_mov_b32_e32 v15, v0
	v_mov_b32_e32 v24, v0
	v_mov_b32_e32 v25, v0
	v_mov_b32_e32 v26, v0
	v_mov_b32_e32 v27, v0
	v_mov_b32_e32 v28, v0
	v_mov_b32_e32 v29, v0
	v_mov_b32_e32 v30, v0
	v_mov_b32_e32 v31, v0
	v_mov_b32_e32 v40, v0
	v_mov_b32_e32 v41, v0
	v_mov_b32_e32 v42, v0
	v_mov_b32_e32 v43, v0
	v_mov_b32_e32 v44, v0
	v_mov_b32_e32 v45, v0
	v_mov_b32_e32 v46, v0
	v_mov_b32_e32 v47, v0
	v_mov_b32_e32 v56, v0
	v_mov_b32_e32 v57, v0
	v_mov_b32_e32 v58, v0
	v_mov_b32_e32 v59, v0
	v_mov_b32_e32 v60, v0
	v_mov_b32_e32 v61, v0
	v_mov_b32_e32 v62, v0
	v_mov_b32_e32 v63, v0
	v_mov_b32_e32 v64, v0
	v_mov_b32_e32 v65, v0
	v_mov_b32_e32 v66, v0
	v_mov_b32_e32 v67, v0
	v_mov_b32_e32 v68, v0
	v_mov_b32_e32 v69, v0
	v_mov_b32_e32 v70, v0
	v_mov_b32_e32 v71, v0
	v_mov_b32_e32 v80, v0
	v_mov_b32_e32 v81, v0
	v_mov_b32_e32 v82, v0
	v_mov_b32_e32 v83, v0
	v_mov_b32_e32 v84, v0
	v_mov_b32_e32 v85, v0
	v_mov_b32_e32 v86, v0
	v_mov_b32_e32 v87, v0
	v_mov_b32_e32 v96, v0
	v_mov_b32_e32 v97, v0
	v_mov_b32_e32 v98, v0
	v_mov_b32_e32 v99, v0
	v_mov_b32_e32 v100, v0
	v_mov_b32_e32 v101, v0
	v_mov_b32_e32 v102, v0
	v_mov_b32_e32 v103, v0
	v_mov_b32_e32 v112, v0
	v_mov_b32_e32 v113, v0
	v_mov_b32_e32 v114, v0
	v_mov_b32_e32 v115, v0
	v_mov_b32_e32 v116, v0
	v_mov_b32_e32 v117, v0
	v_mov_b32_e32 v118, v0
	v_mov_b32_e32 v119, v0
	v_mov_b32_e32 v72, v0
	v_mov_b32_e32 v73, v0
	v_mov_b32_e32 v74, v0
	v_mov_b32_e32 v75, v0
	v_mov_b32_e32 v76, v0
	v_mov_b32_e32 v77, v0
	v_mov_b32_e32 v78, v0
	v_mov_b32_e32 v79, v0
	v_mov_b32_e32 v88, v0
	v_mov_b32_e32 v89, v0
	v_mov_b32_e32 v90, v0
	v_mov_b32_e32 v91, v0
	v_mov_b32_e32 v92, v0
	v_mov_b32_e32 v93, v0
	v_mov_b32_e32 v94, v0
	v_mov_b32_e32 v95, v0
	v_mov_b32_e32 v104, v0
	v_mov_b32_e32 v105, v0
	v_mov_b32_e32 v106, v0
	v_mov_b32_e32 v107, v0
	v_mov_b32_e32 v108, v0
	v_mov_b32_e32 v109, v0
	v_mov_b32_e32 v110, v0
	v_mov_b32_e32 v111, v0
	v_mov_b32_e32 v120, v0
	v_mov_b32_e32 v121, v0
	v_mov_b32_e32 v122, v0
	v_mov_b32_e32 v123, v0
	v_mov_b32_e32 v124, v0
	v_mov_b32_e32 v125, v0
	v_mov_b32_e32 v126, v0
	v_mov_b32_e32 v127, v0
	.p2align 6

.LBB0_1262:
	s_add_u32 s6, s22, 0x100
	v_mov_b32_e32 v0, 0
	s_addc_u32 s15, s23, 0
	s_mov_b32 s46, -2
	v_mov_b32_e32 v1, v0
	v_mov_b32_e32 v2, v0
	v_mov_b32_e32 v3, v0
	v_mov_b32_e32 v4, v0
	v_mov_b32_e32 v5, v0
	v_mov_b32_e32 v6, v0
	v_mov_b32_e32 v7, v0
	v_mov_b32_e32 v12, v0
	v_mov_b32_e32 v13, v0
	v_mov_b32_e32 v14, v0
	v_mov_b32_e32 v15, v0
	v_mov_b32_e32 v20, v0
	v_mov_b32_e32 v21, v0
	v_mov_b32_e32 v22, v0
	v_mov_b32_e32 v23, v0
	v_mov_b32_e32 v28, v0
	v_mov_b32_e32 v29, v0
	v_mov_b32_e32 v30, v0
	v_mov_b32_e32 v31, v0
	v_mov_b32_e32 v36, v0
	v_mov_b32_e32 v37, v0
	v_mov_b32_e32 v38, v0
	v_mov_b32_e32 v39, v0
	v_mov_b32_e32 v44, v0
	v_mov_b32_e32 v45, v0
	v_mov_b32_e32 v46, v0
	v_mov_b32_e32 v47, v0
	v_mov_b32_e32 v52, v0
	v_mov_b32_e32 v53, v0
	v_mov_b32_e32 v54, v0
	v_mov_b32_e32 v55, v0
	v_mov_b32_e32 v8, v0
	v_mov_b32_e32 v9, v0
	v_mov_b32_e32 v10, v0
	v_mov_b32_e32 v11, v0
	v_mov_b32_e32 v16, v0
	v_mov_b32_e32 v17, v0
	v_mov_b32_e32 v18, v0
	v_mov_b32_e32 v19, v0
	v_mov_b32_e32 v24, v0
	v_mov_b32_e32 v25, v0
	v_mov_b32_e32 v26, v0
	v_mov_b32_e32 v27, v0
	v_mov_b32_e32 v32, v0
	v_mov_b32_e32 v33, v0
	v_mov_b32_e32 v34, v0
	v_mov_b32_e32 v35, v0
	v_mov_b32_e32 v40, v0
	v_mov_b32_e32 v41, v0
	v_mov_b32_e32 v42, v0
	v_mov_b32_e32 v43, v0
	v_mov_b32_e32 v48, v0
	v_mov_b32_e32 v49, v0
	v_mov_b32_e32 v50, v0
	v_mov_b32_e32 v51, v0
	v_mov_b32_e32 v56, v0
	v_mov_b32_e32 v57, v0
	v_mov_b32_e32 v58, v0
	v_mov_b32_e32 v59, v0
	v_mov_b32_e32 v60, v0
	v_mov_b32_e32 v61, v0
	v_mov_b32_e32 v62, v0
	v_mov_b32_e32 v63, v0
	v_mov_b32_e32 v64, v0
	v_mov_b32_e32 v65, v0
	v_mov_b32_e32 v66, v0
	v_mov_b32_e32 v67, v0
	v_mov_b32_e32 v68, v0
	v_mov_b32_e32 v69, v0
	v_mov_b32_e32 v70, v0
	v_mov_b32_e32 v71, v0
	v_mov_b32_e32 v76, v0
	v_mov_b32_e32 v77, v0
	v_mov_b32_e32 v78, v0
	v_mov_b32_e32 v79, v0
	v_mov_b32_e32 v84, v0
	v_mov_b32_e32 v85, v0
	v_mov_b32_e32 v86, v0
	v_mov_b32_e32 v87, v0
	v_mov_b32_e32 v92, v0
	v_mov_b32_e32 v93, v0
	v_mov_b32_e32 v94, v0
	v_mov_b32_e32 v95, v0
	v_mov_b32_e32 v100, v0
	v_mov_b32_e32 v101, v0
	v_mov_b32_e32 v102, v0
	v_mov_b32_e32 v103, v0
	v_mov_b32_e32 v108, v0
	v_mov_b32_e32 v109, v0
	v_mov_b32_e32 v110, v0
	v_mov_b32_e32 v111, v0
	v_mov_b32_e32 v116, v0
	v_mov_b32_e32 v117, v0
	v_mov_b32_e32 v118, v0
	v_mov_b32_e32 v119, v0
	v_mov_b32_e32 v72, v0
	v_mov_b32_e32 v73, v0
	v_mov_b32_e32 v74, v0
	v_mov_b32_e32 v75, v0
	v_mov_b32_e32 v80, v0
	v_mov_b32_e32 v81, v0
	v_mov_b32_e32 v82, v0
	v_mov_b32_e32 v83, v0
	v_mov_b32_e32 v88, v0
	v_mov_b32_e32 v89, v0
	v_mov_b32_e32 v90, v0
	v_mov_b32_e32 v91, v0
	v_mov_b32_e32 v96, v0
	v_mov_b32_e32 v97, v0
	v_mov_b32_e32 v98, v0
	v_mov_b32_e32 v99, v0
	v_mov_b32_e32 v104, v0
	v_mov_b32_e32 v105, v0
	v_mov_b32_e32 v106, v0
	v_mov_b32_e32 v107, v0
	v_mov_b32_e32 v112, v0
	v_mov_b32_e32 v113, v0
	v_mov_b32_e32 v114, v0
	v_mov_b32_e32 v115, v0
	v_mov_b32_e32 v120, v0
	v_mov_b32_e32 v121, v0
	v_mov_b32_e32 v122, v0
	v_mov_b32_e32 v123, v0
	v_mov_b32_e32 v124, v0
	v_mov_b32_e32 v125, v0
	v_mov_b32_e32 v126, v0
	v_mov_b32_e32 v127, v0
	.p2align 6

.LBB0_1339:
	s_ashr_i32 s23, s22, 31
	s_lshl_b64 s[24:25], s[22:23], 21
	s_add_u32 s24, s38, s24
	s_addc_u32 s25, s39, s25
	s_and_b64 s[26:27], s[4:5], exec
	s_cselect_b32 s23, s25, s11
	s_cselect_b32 s54, s24, s10
	s_ashr_i32 s26, s22, 4
	s_ashr_i32 s27, s26, 31
	s_lshl_b64 s[26:27], s[26:27], 23
	s_add_u32 s28, s40, s26
	s_addc_u32 s29, s41, s27
	s_ashr_i32 s21, s20, 31
	s_lshl_b64 s[26:27], s[20:21], 21
	s_add_u32 s26, s28, s26
	s_addc_u32 s27, s29, s27
	s_and_b64 s[28:29], s[4:5], exec
	s_cselect_b32 s21, s27, s9
	s_cselect_b32 s55, s26, s8
	s_add_u32 s56, s8, 0x100
	s_addc_u32 s57, s9, 0
	s_mov_b32 s58, -2
	s_mov_b64 s[28:29], 0x1000
	v_mov_b64_e32 v[144:145], v[138:139]
	v_mov_b64_e32 v[146:147], v[136:137]
	.p2align 6

.LBB0_1434:
	s_ashr_i32 s19, s18, 31
	s_lshl_b64 s[20:21], s[18:19], 19
	s_add_u32 s20, s33, s20
	s_addc_u32 s21, s36, s21
	s_and_b64 s[22:23], s[4:5], exec
	s_cselect_b32 s1, s21, s25
	s_cselect_b32 s19, s20, s24
	s_ashr_i32 s22, s18, 4
	s_ashr_i32 s23, s22, 31
	s_lshl_b64 s[22:23], s[22:23], 11
	s_add_u32 s28, s37, s22
	s_addc_u32 s29, s38, s23
	s_ashr_i32 s17, s16, 31
	s_lshl_b64 s[22:23], s[16:17], 21
	s_add_u32 s22, s28, s22
	s_addc_u32 s23, s29, s23
	s_and_b64 s[28:29], s[4:5], exec
	s_cselect_b32 s17, s23, s27
	s_cselect_b32 s30, s22, s26
	s_add_u32 s24, s24, 0x40080
	s_addc_u32 s25, s25, 0
	s_add_u32 s31, s26, 0x100
	v_mov_b32_e32 v0, 0
	s_addc_u32 s34, s27, 0
	s_mov_b32 s35, -2
	s_waitcnt lgkmcnt(0)
	v_mov_b32_e32 v1, v0
	v_mov_b32_e32 v2, v0
	v_mov_b32_e32 v3, v0
	v_mov_b32_e32 v4, v0
	v_mov_b32_e32 v5, v0
	v_mov_b32_e32 v6, v0
	v_mov_b32_e32 v7, v0
	v_mov_b32_e32 v16, v0
	v_mov_b32_e32 v17, v0
	v_mov_b32_e32 v18, v0
	v_mov_b32_e32 v19, v0
	v_mov_b32_e32 v20, v0
	v_mov_b32_e32 v21, v0
	v_mov_b32_e32 v22, v0
	v_mov_b32_e32 v23, v0
	v_mov_b32_e32 v32, v0
	v_mov_b32_e32 v33, v0
	v_mov_b32_e32 v34, v0
	v_mov_b32_e32 v35, v0
	v_mov_b32_e32 v36, v0
	v_mov_b32_e32 v37, v0
	v_mov_b32_e32 v38, v0
	v_mov_b32_e32 v39, v0
	v_mov_b32_e32 v48, v0
	v_mov_b32_e32 v49, v0
	v_mov_b32_e32 v50, v0
	v_mov_b32_e32 v51, v0
	v_mov_b32_e32 v52, v0
	v_mov_b32_e32 v53, v0
	v_mov_b32_e32 v54, v0
	v_mov_b32_e32 v55, v0
	v_mov_b32_e32 v8, v0
	v_mov_b32_e32 v9, v0
	v_mov_b32_e32 v10, v0
	v_mov_b32_e32 v11, v0
	v_mov_b32_e32 v12, v0
	v_mov_b32_e32 v13, v0
	v_mov_b32_e32 v14, v0
	v_mov_b32_e32 v15, v0
	v_mov_b32_e32 v24, v0
	v_mov_b32_e32 v25, v0
	v_mov_b32_e32 v26, v0
	v_mov_b32_e32 v27, v0
	v_mov_b32_e32 v28, v0
	v_mov_b32_e32 v29, v0
	v_mov_b32_e32 v30, v0
	v_mov_b32_e32 v31, v0
	v_mov_b32_e32 v40, v0
	v_mov_b32_e32 v41, v0
	v_mov_b32_e32 v42, v0
	v_mov_b32_e32 v43, v0
	v_mov_b32_e32 v44, v0
	v_mov_b32_e32 v45, v0
	v_mov_b32_e32 v46, v0
	v_mov_b32_e32 v47, v0
	v_mov_b32_e32 v56, v0
	v_mov_b32_e32 v57, v0
	v_mov_b32_e32 v58, v0
	v_mov_b32_e32 v59, v0
	v_mov_b32_e32 v60, v0
	v_mov_b32_e32 v61, v0
	v_mov_b32_e32 v62, v0
	v_mov_b32_e32 v63, v0
	v_mov_b32_e32 v64, v0
	v_mov_b32_e32 v65, v0
	v_mov_b32_e32 v66, v0
	v_mov_b32_e32 v67, v0
	v_mov_b32_e32 v68, v0
	v_mov_b32_e32 v69, v0
	v_mov_b32_e32 v70, v0
	v_mov_b32_e32 v71, v0
	v_mov_b32_e32 v80, v0
	v_mov_b32_e32 v81, v0
	v_mov_b32_e32 v82, v0
	v_mov_b32_e32 v83, v0
	v_mov_b32_e32 v84, v0
	v_mov_b32_e32 v85, v0
	v_mov_b32_e32 v86, v0
	v_mov_b32_e32 v87, v0
	v_mov_b32_e32 v96, v0
	v_mov_b32_e32 v97, v0
	v_mov_b32_e32 v98, v0
	v_mov_b32_e32 v99, v0
	v_mov_b32_e32 v100, v0
	v_mov_b32_e32 v101, v0
	v_mov_b32_e32 v102, v0
	v_mov_b32_e32 v103, v0
	v_mov_b32_e32 v112, v0
	v_mov_b32_e32 v113, v0
	v_mov_b32_e32 v114, v0
	v_mov_b32_e32 v115, v0
	v_mov_b32_e32 v116, v0
	v_mov_b32_e32 v117, v0
	v_mov_b32_e32 v118, v0
	v_mov_b32_e32 v119, v0
	v_mov_b32_e32 v72, v0
	v_mov_b32_e32 v73, v0
	v_mov_b32_e32 v74, v0
	v_mov_b32_e32 v75, v0
	v_mov_b32_e32 v76, v0
	v_mov_b32_e32 v77, v0
	v_mov_b32_e32 v78, v0
	v_mov_b32_e32 v79, v0
	v_mov_b32_e32 v88, v0
	v_mov_b32_e32 v89, v0
	v_mov_b32_e32 v90, v0
	v_mov_b32_e32 v91, v0
	v_mov_b32_e32 v92, v0
	v_mov_b32_e32 v93, v0
	v_mov_b32_e32 v94, v0
	v_mov_b32_e32 v95, v0
	v_mov_b32_e32 v104, v0
	v_mov_b32_e32 v105, v0
	v_mov_b32_e32 v106, v0
	v_mov_b32_e32 v107, v0
	v_mov_b32_e32 v108, v0
	v_mov_b32_e32 v109, v0
	v_mov_b32_e32 v110, v0
	v_mov_b32_e32 v111, v0
	v_mov_b32_e32 v120, v0
	v_mov_b32_e32 v121, v0
	v_mov_b32_e32 v122, v0
	v_mov_b32_e32 v123, v0
	v_mov_b32_e32 v124, v0
	v_mov_b32_e32 v125, v0
	v_mov_b32_e32 v126, v0
	v_mov_b32_e32 v127, v0
	.p2align 6

.LBB0_1542:
	s_ashr_i32 s13, s12, 31
	s_lshl_b64 s[14:15], s[12:13], 21
	s_add_u32 s14, s31, s14
	s_addc_u32 s15, s33, s15
	s_and_b64 s[16:17], s[2:3], exec
	s_cselect_b32 s13, s15, s21
	s_cselect_b32 s50, s14, s20
	s_ashr_i32 s11, s10, 31
	s_lshl_b64 s[16:17], s[10:11], 21
	s_add_u32 s16, s34, s16
	s_addc_u32 s17, s35, s17
	s_and_b64 s[24:25], s[2:3], exec
	s_cselect_b32 s11, s17, s23
	s_cselect_b32 s51, s16, s22
	s_add_u32 s52, s22, 0x1000
	v_mov_b32_e32 v0, 0
	s_addc_u32 s53, s23, 0
	s_mov_b32 s54, -2
	v_mov_b32_e32 v1, v0
	v_mov_b32_e32 v2, v0
	v_mov_b32_e32 v3, v0
	v_mov_b32_e32 v4, v0
	v_mov_b32_e32 v5, v0
	v_mov_b32_e32 v6, v0
	v_mov_b32_e32 v7, v0
	v_mov_b32_e32 v16, v0
	v_mov_b32_e32 v17, v0
	v_mov_b32_e32 v18, v0
	v_mov_b32_e32 v19, v0
	v_mov_b32_e32 v20, v0
	v_mov_b32_e32 v21, v0
	v_mov_b32_e32 v22, v0
	v_mov_b32_e32 v23, v0
	v_mov_b32_e32 v32, v0
	v_mov_b32_e32 v33, v0
	v_mov_b32_e32 v34, v0
	v_mov_b32_e32 v35, v0
	v_mov_b32_e32 v36, v0
	v_mov_b32_e32 v37, v0
	v_mov_b32_e32 v38, v0
	v_mov_b32_e32 v39, v0
	v_mov_b32_e32 v48, v0
	v_mov_b32_e32 v49, v0
	v_mov_b32_e32 v50, v0
	v_mov_b32_e32 v51, v0
	v_mov_b32_e32 v52, v0
	v_mov_b32_e32 v53, v0
	v_mov_b32_e32 v54, v0
	v_mov_b32_e32 v55, v0
	v_mov_b32_e32 v8, v0
	v_mov_b32_e32 v9, v0
	v_mov_b32_e32 v10, v0
	v_mov_b32_e32 v11, v0
	v_mov_b32_e32 v12, v0
	v_mov_b32_e32 v13, v0
	v_mov_b32_e32 v14, v0
	v_mov_b32_e32 v15, v0
	v_mov_b32_e32 v24, v0
	v_mov_b32_e32 v25, v0
	v_mov_b32_e32 v26, v0
	v_mov_b32_e32 v27, v0
	v_mov_b32_e32 v28, v0
	v_mov_b32_e32 v29, v0
	v_mov_b32_e32 v30, v0
	v_mov_b32_e32 v31, v0
	v_mov_b32_e32 v40, v0
	v_mov_b32_e32 v41, v0
	v_mov_b32_e32 v42, v0
	v_mov_b32_e32 v43, v0
	v_mov_b32_e32 v44, v0
	v_mov_b32_e32 v45, v0
	v_mov_b32_e32 v46, v0
	v_mov_b32_e32 v47, v0
	v_mov_b32_e32 v56, v0
	v_mov_b32_e32 v57, v0
	v_mov_b32_e32 v58, v0
	v_mov_b32_e32 v59, v0
	v_mov_b32_e32 v60, v0
	v_mov_b32_e32 v61, v0
	v_mov_b32_e32 v62, v0
	v_mov_b32_e32 v63, v0
	v_mov_b32_e32 v64, v0
	v_mov_b32_e32 v65, v0
	v_mov_b32_e32 v66, v0
	v_mov_b32_e32 v67, v0
	v_mov_b32_e32 v68, v0
	v_mov_b32_e32 v69, v0
	v_mov_b32_e32 v70, v0
	v_mov_b32_e32 v71, v0
	v_mov_b32_e32 v80, v0
	v_mov_b32_e32 v81, v0
	v_mov_b32_e32 v82, v0
	v_mov_b32_e32 v83, v0
	v_mov_b32_e32 v84, v0
	v_mov_b32_e32 v85, v0
	v_mov_b32_e32 v86, v0
	v_mov_b32_e32 v87, v0
	v_mov_b32_e32 v96, v0
	v_mov_b32_e32 v97, v0
	v_mov_b32_e32 v98, v0
	v_mov_b32_e32 v99, v0
	v_mov_b32_e32 v100, v0
	v_mov_b32_e32 v101, v0
	v_mov_b32_e32 v102, v0
	v_mov_b32_e32 v103, v0
	v_mov_b32_e32 v112, v0
	v_mov_b32_e32 v113, v0
	v_mov_b32_e32 v114, v0
	v_mov_b32_e32 v115, v0
	v_mov_b32_e32 v116, v0
	v_mov_b32_e32 v117, v0
	v_mov_b32_e32 v118, v0
	v_mov_b32_e32 v119, v0
	v_mov_b32_e32 v72, v0
	v_mov_b32_e32 v73, v0
	v_mov_b32_e32 v74, v0
	v_mov_b32_e32 v75, v0
	v_mov_b32_e32 v76, v0
	v_mov_b32_e32 v77, v0
	v_mov_b32_e32 v78, v0
	v_mov_b32_e32 v79, v0
	v_mov_b32_e32 v88, v0
	v_mov_b32_e32 v89, v0
	v_mov_b32_e32 v90, v0
	v_mov_b32_e32 v91, v0
	v_mov_b32_e32 v92, v0
	v_mov_b32_e32 v93, v0
	v_mov_b32_e32 v94, v0
	v_mov_b32_e32 v95, v0
	v_mov_b32_e32 v104, v0
	v_mov_b32_e32 v105, v0
	v_mov_b32_e32 v106, v0
	v_mov_b32_e32 v107, v0
	v_mov_b32_e32 v108, v0
	v_mov_b32_e32 v109, v0
	v_mov_b32_e32 v110, v0
	v_mov_b32_e32 v111, v0
	v_mov_b32_e32 v120, v0
	v_mov_b32_e32 v121, v0
	v_mov_b32_e32 v122, v0
	v_mov_b32_e32 v123, v0
	v_mov_b32_e32 v124, v0
	v_mov_b32_e32 v125, v0
	v_mov_b32_e32 v126, v0
	v_mov_b32_e32 v127, v0
	.p2align 6

.LBB0_1624:
	s_sub_i32 s17, s52, 32
	s_ashr_i32 s18, s52, 31
	s_cmp_lt_i32 s52, 32
	s_cselect_b32 s19, s18, 0
	s_cselect_b32 s18, s52, s17
	s_cselect_b32 s17, s31, s34
	s_cselect_b32 s20, s30, s33
	s_lshl_b64 s[18:19], s[18:19], 23
	s_add_u32 s18, s20, s18
	s_addc_u32 s19, s17, s19
	s_and_b64 s[20:21], s[4:5], exec
	s_cselect_b32 s29, s19, s23
	s_cselect_b32 s53, s18, s22
	s_ashr_i32 s17, s16, 31
	s_lshl_b64 s[20:21], s[16:17], 23
	s_add_u32 s20, s35, s20
	s_addc_u32 s21, s36, s21
	s_and_b64 s[26:27], s[4:5], exec
	s_cselect_b32 s17, s21, s25
	s_cselect_b32 s54, s20, s24
	s_add_u32 s22, s22, 0x400800
	s_addc_u32 s23, s23, 0
	s_add_u32 s55, s24, 0x1000
	v_mov_b32_e32 v0, 0
	s_addc_u32 s56, s25, 0
	s_mov_b32 s57, -2
	s_waitcnt lgkmcnt(0)
	v_mov_b32_e32 v1, v0
	v_mov_b32_e32 v2, v0
	v_mov_b32_e32 v3, v0
	v_mov_b32_e32 v4, v0
	v_mov_b32_e32 v5, v0
	v_mov_b32_e32 v6, v0
	v_mov_b32_e32 v7, v0
	v_mov_b32_e32 v16, v0
	v_mov_b32_e32 v17, v0
	v_mov_b32_e32 v18, v0
	v_mov_b32_e32 v19, v0
	v_mov_b32_e32 v20, v0
	v_mov_b32_e32 v21, v0
	v_mov_b32_e32 v22, v0
	v_mov_b32_e32 v23, v0
	v_mov_b32_e32 v32, v0
	v_mov_b32_e32 v33, v0
	v_mov_b32_e32 v34, v0
	v_mov_b32_e32 v35, v0
	v_mov_b32_e32 v36, v0
	v_mov_b32_e32 v37, v0
	v_mov_b32_e32 v38, v0
	v_mov_b32_e32 v39, v0
	v_mov_b32_e32 v48, v0
	v_mov_b32_e32 v49, v0
	v_mov_b32_e32 v50, v0
	v_mov_b32_e32 v51, v0
	v_mov_b32_e32 v52, v0
	v_mov_b32_e32 v53, v0
	v_mov_b32_e32 v54, v0
	v_mov_b32_e32 v55, v0
	v_mov_b32_e32 v8, v0
	v_mov_b32_e32 v9, v0
	v_mov_b32_e32 v10, v0
	v_mov_b32_e32 v11, v0
	v_mov_b32_e32 v12, v0
	v_mov_b32_e32 v13, v0
	v_mov_b32_e32 v14, v0
	v_mov_b32_e32 v15, v0
	v_mov_b32_e32 v24, v0
	v_mov_b32_e32 v25, v0
	v_mov_b32_e32 v26, v0
	v_mov_b32_e32 v27, v0
	v_mov_b32_e32 v28, v0
	v_mov_b32_e32 v29, v0
	v_mov_b32_e32 v30, v0
	v_mov_b32_e32 v31, v0
	v_mov_b32_e32 v40, v0
	v_mov_b32_e32 v41, v0
	v_mov_b32_e32 v42, v0
	v_mov_b32_e32 v43, v0
	v_mov_b32_e32 v44, v0
	v_mov_b32_e32 v45, v0
	v_mov_b32_e32 v46, v0
	v_mov_b32_e32 v47, v0
	v_mov_b32_e32 v56, v0
	v_mov_b32_e32 v57, v0
	v_mov_b32_e32 v58, v0
	v_mov_b32_e32 v59, v0
	v_mov_b32_e32 v60, v0
	v_mov_b32_e32 v61, v0
	v_mov_b32_e32 v62, v0
	v_mov_b32_e32 v63, v0
	v_mov_b32_e32 v64, v0
	v_mov_b32_e32 v65, v0
	v_mov_b32_e32 v66, v0
	v_mov_b32_e32 v67, v0
	v_mov_b32_e32 v68, v0
	v_mov_b32_e32 v69, v0
	v_mov_b32_e32 v70, v0
	v_mov_b32_e32 v71, v0
	v_mov_b32_e32 v80, v0
	v_mov_b32_e32 v81, v0
	v_mov_b32_e32 v82, v0
	v_mov_b32_e32 v83, v0
	v_mov_b32_e32 v84, v0
	v_mov_b32_e32 v85, v0
	v_mov_b32_e32 v86, v0
	v_mov_b32_e32 v87, v0
	v_mov_b32_e32 v96, v0
	v_mov_b32_e32 v97, v0
	v_mov_b32_e32 v98, v0
	v_mov_b32_e32 v99, v0
	v_mov_b32_e32 v100, v0
	v_mov_b32_e32 v101, v0
	v_mov_b32_e32 v102, v0
	v_mov_b32_e32 v103, v0
	v_mov_b32_e32 v112, v0
	v_mov_b32_e32 v113, v0
	v_mov_b32_e32 v114, v0
	v_mov_b32_e32 v115, v0
	v_mov_b32_e32 v116, v0
	v_mov_b32_e32 v117, v0
	v_mov_b32_e32 v118, v0
	v_mov_b32_e32 v119, v0
	v_mov_b32_e32 v72, v0
	v_mov_b32_e32 v73, v0
	v_mov_b32_e32 v74, v0
	v_mov_b32_e32 v75, v0
	v_mov_b32_e32 v76, v0
	v_mov_b32_e32 v77, v0
	v_mov_b32_e32 v78, v0
	v_mov_b32_e32 v79, v0
	v_mov_b32_e32 v88, v0
	v_mov_b32_e32 v89, v0
	v_mov_b32_e32 v90, v0
	v_mov_b32_e32 v91, v0
	v_mov_b32_e32 v92, v0
	v_mov_b32_e32 v93, v0
	v_mov_b32_e32 v94, v0
	v_mov_b32_e32 v95, v0
	v_mov_b32_e32 v104, v0
	v_mov_b32_e32 v105, v0
	v_mov_b32_e32 v106, v0
	v_mov_b32_e32 v107, v0
	v_mov_b32_e32 v108, v0
	v_mov_b32_e32 v109, v0
	v_mov_b32_e32 v110, v0
	v_mov_b32_e32 v111, v0
	v_mov_b32_e32 v120, v0
	v_mov_b32_e32 v121, v0
	v_mov_b32_e32 v122, v0
	v_mov_b32_e32 v123, v0
	v_mov_b32_e32 v124, v0
	v_mov_b32_e32 v125, v0
	v_mov_b32_e32 v126, v0
	v_mov_b32_e32 v127, v0
	.p2align 6
